# MLP-up (P10) epilogue stores of the 256 MB hidden activations carry the nt hint so they do not displace the GEMM operands in L2
# baseline (speedup 1.0000x reference)
; #define EPI_FOR_ROWS for (int ai = 0; ai < 2; ++ai) _Pragma("unroll") for (int m = 0; m < 4; ++m)
; __device__ __forceinline__ u32x4 pack8(const f32x4 a, const f32x4 b) { u32x4 w; w.x = cvt_pk_bf16(a[0], a[1]); w.y = cvt_pk_bf16(a[2], a[3]); w.z = cvt_pk_bf16(b[0], b[1]); w.w = cvt_pk_bf16(b[2], b[3]); return w; }
;     __device__ __forceinline__ void piece(size_t row, int col, f32x4 v0, f32x4 v1, const f32x4 a0, const f32x4 a1, const f32x4 b0, const f32x4 b1, const f32x4 c0, const f32x4 c1,
;                                           float mean, float rstd, float& s, float& ss) const {
;     ...
;         if constexpr (MODE == 4) { v0 = (v0 - a0 * mean) * rstd + b0; v1 = (v1 - a1 * mean) * rstd + b1;
; #pragma unroll
;             for (int e = 0; e < 4; ++e) { const float x = fmaxf(v0[e], 0.f), y = fmaxf(v1[e], 0.f); v0[e] = x * x; v1[e] = y * y; } }
;         if constexpr (PROD) {
; #pragma unroll
;             for (int e = 0; e < 4; ++e) { s += v0[e] + v1[e]; ss += v0[e] * v0[e] + v1[e] * v1[e]; } }
;         if constexpr (MODE == 5) { float* o = (float*)O + row * ldo + col; *(f32x4*)o = v0; *(f32x4*)(o + 4) = v1; }
;         else *(u32x4*)((bf16_t*)O + row * ldo + col) = pack8(v0, v1);
;     __device__ __forceinline__ void operator()(const f32x4 (&acc)[2][2][4][2], const Unit& u, int wr, int wc, int fr_, int fq_, LAS unsigned char* ldsx) const {
;     ...
;         EPI_FOR_ROWS {
;             const int rl = ai * HALF + wr * 64 + m * 16 + fr; const size_t row = (size_t)u.row0 + rl;
;             float mean = 0.f, rstd = 0.f; if constexpr (CONS) { const f32x2 st = X[rl]; mean = st.x; rstd = st.y; }
;             float s = 0.f, ss = 0.f;
; #pragma unroll
;             for (int bj = 0; bj < 2; ++bj) piece(row, colb + bj * HALF, acc[ai][bj][m][0], acc[ai][bj][m][1], av[bj][0], av[bj][1], bv[bj][0], bv[bj][1], cv[bj][0], cv[bj][1], mean, rstd, s, ss);
;             if constexpr (PROD) { s += __shfl_xor(s, 16); ss += __shfl_xor(ss, 16); s += __shfl_xor(s, 32); ss += __shfl_xor(ss, 32);
;                 if (fq == 0) st_out[row * 16 + (u.col0 >> 8) * 4 + wc] = (f32x2){s, ss}; }
.LBB0_1381:
	s_cmp_eq_u32 s20, s10
	v_mov_b32_e32 v174, v178
	v_mov_b32_e32 v128, v179
	s_cselect_b32 s25, 0, 0x800
	s_add_i32 s21, s36, s60
	s_add_i32 s25, s25, 0
	v_lshl_add_u32 v176, v128, 3, s21
	v_ashrrev_i32_e32 v177, 31, v176
	v_lshlrev_b64 v[132:133], 2, v[176:177]
	v_lshl_add_u64 v[128:129], s[0:1], 0, v[132:133]
	global_load_dwordx4 v[148:151], v[128:129], off
	global_load_dwordx4 v[144:147], v[128:129], off offset:16
	global_load_dwordx4 v[136:139], v[128:129], off offset:512
	s_nop 0
	global_load_dwordx4 v[128:131], v[128:129], off offset:528
	v_lshl_add_u64 v[132:133], s[8:9], 0, v[132:133]
	global_load_dwordx4 v[156:159], v[132:133], off
	global_load_dwordx4 v[152:155], v[132:133], off offset:16
	global_load_dwordx4 v[140:143], v[132:133], off offset:512
	s_nop 0
	global_load_dwordx4 v[132:135], v[132:133], off offset:528
	v_add_u32_e32 v174, s43, v174
	s_ashr_i32 s21, s20, 31
	v_lshl_add_u32 v184, v174, 3, s25
	v_ashrrev_i32_e32 v175, 31, v174
	v_lshl_add_u64 v[188:189], v[174:175], 0, s[20:21]
	v_add_u32_e32 v175, 0x20000, v184
	ds_read2_b64 v[184:187], v175 offset1:16
	v_lshlrev_b64 v[188:189], 13, v[188:189]
	v_lshlrev_b64 v[176:177], 1, v[176:177]
	v_lshl_add_u64 v[188:189], s[44:45], 0, v[188:189]
	v_lshl_add_u64 v[192:193], v[188:189], 0, v[176:177]
	s_andn2_b64 vcc, exec, s[28:29]
	s_waitcnt vmcnt(0)
	v_xor_b32_e32 v151, 0x80000000, v151
	v_xor_b32_e32 v150, 0x80000000, v150
	s_waitcnt lgkmcnt(0)
	v_pk_fma_f32 v[188:189], v[148:149], v[184:185], v[124:125] op_sel_hi:[1,0,1] neg_lo:[1,0,0] neg_hi:[1,0,0]
	v_xor_b32_e32 v125, 0x80000000, v147
	v_xor_b32_e32 v124, 0x80000000, v146
	v_pk_fma_f32 v[146:147], v[144:145], v[184:185], v[120:121] op_sel_hi:[1,0,1] neg_lo:[1,0,0] neg_hi:[1,0,0]
	v_xor_b32_e32 v121, 0x80000000, v139
	v_xor_b32_e32 v120, 0x80000000, v138
	v_pk_fma_f32 v[138:139], v[136:137], v[184:185], v[116:117] op_sel_hi:[1,0,1] neg_lo:[1,0,0] neg_hi:[1,0,0]
	v_xor_b32_e32 v117, 0x80000000, v131
	v_xor_b32_e32 v116, 0x80000000, v130
	v_pk_fma_f32 v[112:113], v[128:129], v[184:185], v[112:113] op_sel_hi:[1,0,1] neg_lo:[1,0,0] neg_hi:[1,0,0]
	v_pk_fma_f32 v[126:127], v[150:151], v[184:185], v[126:127] op_sel_hi:[1,0,1]
	v_pk_fma_f32 v[130:131], v[184:185], v[188:189], v[156:157] op_sel:[1,0,0]
	v_pk_fma_f32 v[122:123], v[124:125], v[184:185], v[122:123] op_sel_hi:[1,0,1]
	v_pk_fma_f32 v[118:119], v[120:121], v[184:185], v[118:119] op_sel_hi:[1,0,1]
	v_pk_fma_f32 v[114:115], v[116:117], v[184:185], v[114:115] op_sel_hi:[1,0,1]
	v_pk_fma_f32 v[112:113], v[184:185], v[112:113], v[132:133] op_sel:[1,0,0]
	v_pk_fma_f32 v[146:147], v[184:185], v[146:147], v[152:153] op_sel:[1,0,0]
	v_pk_fma_f32 v[126:127], v[184:185], v[126:127], v[158:159] op_sel:[1,0,0]
	v_pk_fma_f32 v[122:123], v[184:185], v[122:123], v[154:155] op_sel:[1,0,0]
	v_max_f32_e32 v130, 0, v130
	v_max_f32_e32 v131, 0, v131
	v_pk_fma_f32 v[118:119], v[184:185], v[118:119], v[142:143] op_sel:[1,0,0]
	v_pk_fma_f32 v[114:115], v[184:185], v[114:115], v[134:135] op_sel:[1,0,0]
	v_max_f32_e32 v112, 0, v112
	v_max_f32_e32 v113, 0, v113
	v_pk_fma_f32 v[106:107], v[124:125], v[186:187], v[106:107] op_sel_hi:[1,0,1]
	v_pk_fma_f32 v[104:105], v[144:145], v[186:187], v[104:105] op_sel_hi:[1,0,1] neg_lo:[1,0,0] neg_hi:[1,0,0]
	v_pk_fma_f32 v[138:139], v[184:185], v[138:139], v[140:141] op_sel:[1,0,0]
	v_max_f32_e32 v146, 0, v146
	v_max_f32_e32 v147, 0, v147
	v_mul_f32_e32 v130, v130, v130
	v_mul_f32_e32 v131, v131, v131
	v_max_f32_e32 v126, 0, v126
	v_max_f32_e32 v122, 0, v122
	v_max_f32_e32 v127, 0, v127
	v_max_f32_e32 v123, 0, v123
	v_mul_f32_e32 v184, v112, v112
	v_mul_f32_e32 v185, v113, v113
	v_max_f32_e32 v113, 0, v118
	v_max_f32_e32 v115, 0, v115
	v_cvt_pk_bf16_f32 v112, v130, v131
	v_pk_fma_f32 v[110:111], v[150:151], v[186:187], v[110:111] op_sel_hi:[1,0,1]
	v_pk_fma_f32 v[108:109], v[148:149], v[186:187], v[108:109] op_sel_hi:[1,0,1] neg_lo:[1,0,0] neg_hi:[1,0,0]
	v_pk_fma_f32 v[106:107], v[186:187], v[106:107], v[154:155] op_sel:[1,0,0]
	v_pk_fma_f32 v[104:105], v[186:187], v[104:105], v[152:153] op_sel:[1,0,0]
	v_mul_f32_e32 v146, v146, v146
	v_mul_f32_e32 v147, v147, v147
	v_max_f32_e32 v118, 0, v114
	v_mul_f32_e32 v126, v126, v126
	v_mul_f32_e32 v122, v122, v122
	v_mul_f32_e32 v127, v127, v127
	v_mul_f32_e32 v123, v123, v123
	v_cvt_pk_bf16_f32 v114, v146, v147
	v_mul_f32_e32 v130, v113, v113
	v_mul_f32_e32 v131, v115, v115
	v_cvt_pk_bf16_f32 v113, v126, v127
	v_cvt_pk_bf16_f32 v115, v122, v123
	global_store_dwordx4 v[192:193], v[112:115], off nt
	v_pk_fma_f32 v[110:111], v[186:187], v[110:111], v[158:159] op_sel:[1,0,0]
	v_pk_fma_f32 v[108:109], v[186:187], v[108:109], v[156:157] op_sel:[1,0,0]
	v_add_u32_e32 v112, 16, v174
	v_max_f32_e32 v104, 0, v104
	v_max_f32_e32 v105, 0, v105
	v_max_f32_e32 v106, 0, v106
	v_ashrrev_i32_e32 v113, 31, v112
	v_max_f32_e32 v108, 0, v108
	v_mul_f32_e32 v114, v104, v104
	v_max_f32_e32 v104, 0, v109
	v_mul_f32_e32 v109, v105, v105
	v_max_f32_e32 v105, 0, v110
	v_mul_f32_e32 v110, v106, v106
	v_max_f32_e32 v106, 0, v111
	v_lshl_add_u64 v[112:113], v[112:113], 0, s[20:21]
	v_mul_f32_e32 v108, v108, v108
	v_mul_f32_e32 v104, v104, v104
	v_mul_f32_e32 v105, v105, v105
	v_mul_f32_e32 v106, v106, v106
	v_cvt_pk_bf16_f32 v104, v108, v104
	v_cvt_pk_bf16_f32 v105, v105, v106
	v_cvt_pk_bf16_f32 v106, v114, v109
	v_lshlrev_b64 v[108:109], 13, v[112:113]
	v_pk_fma_f32 v[98:99], v[116:117], v[186:187], v[98:99] op_sel_hi:[1,0,1]
	v_pk_fma_f32 v[96:97], v[128:129], v[186:187], v[96:97] op_sel_hi:[1,0,1] neg_lo:[1,0,0] neg_hi:[1,0,0]
	v_max_f32_e32 v107, 0, v107
	v_lshl_add_u64 v[108:109], s[44:45], 0, v[108:109]
; #define EPI_FOR_ROWS for (int ai = 0; ai < 2; ++ai) _Pragma("unroll") for (int m = 0; m < 4; ++m)
; __device__ __forceinline__ u32x4 pack8(const f32x4 a, const f32x4 b) { u32x4 w; w.x = cvt_pk_bf16(a[0], a[1]); w.y = cvt_pk_bf16(a[2], a[3]); w.z = cvt_pk_bf16(b[0], b[1]); w.w = cvt_pk_bf16(b[2], b[3]); return w; }
;     __device__ __forceinline__ void piece(size_t row, int col, f32x4 v0, f32x4 v1, const f32x4 a0, const f32x4 a1, const f32x4 b0, const f32x4 b1, const f32x4 c0, const f32x4 c1,
;                                           float mean, float rstd, float& s, float& ss) const {
;     ...
;         if constexpr (MODE == 4) { v0 = (v0 - a0 * mean) * rstd + b0; v1 = (v1 - a1 * mean) * rstd + b1;
; #pragma unroll
;             for (int e = 0; e < 4; ++e) { const float x = fmaxf(v0[e], 0.f), y = fmaxf(v1[e], 0.f); v0[e] = x * x; v1[e] = y * y; } }
;         if constexpr (PROD) {
; #pragma unroll
;             for (int e = 0; e < 4; ++e) { s += v0[e] + v1[e]; ss += v0[e] * v0[e] + v1[e] * v1[e]; } }
;         if constexpr (MODE == 5) { float* o = (float*)O + row * ldo + col; *(f32x4*)o = v0; *(f32x4*)(o + 4) = v1; }
;         else *(u32x4*)((bf16_t*)O + row * ldo + col) = pack8(v0, v1);
;     __device__ __forceinline__ void operator()(const f32x4 (&acc)[2][2][4][2], const Unit& u, int wr, int wc, int fr_, int fq_, LAS unsigned char* ldsx) const {
;     ...
;         EPI_FOR_ROWS {
;             const int rl = ai * HALF + wr * 64 + m * 16 + fr; const size_t row = (size_t)u.row0 + rl;
;             float mean = 0.f, rstd = 0.f; if constexpr (CONS) { const f32x2 st = X[rl]; mean = st.x; rstd = st.y; }
;             float s = 0.f, ss = 0.f;
; #pragma unroll
;             for (int bj = 0; bj < 2; ++bj) piece(row, colb + bj * HALF, acc[ai][bj][m][0], acc[ai][bj][m][1], av[bj][0], av[bj][1], bv[bj][0], bv[bj][1], cv[bj][0], cv[bj][1], mean, rstd, s, ss);
;             if constexpr (PROD) { s += __shfl_xor(s, 16); ss += __shfl_xor(ss, 16); s += __shfl_xor(s, 32); ss += __shfl_xor(ss, 32);
;                 if (fq == 0) st_out[row * 16 + (u.col0 >> 8) * 4 + wc] = (f32x2){s, ss}; }
	v_pk_fma_f32 v[102:103], v[120:121], v[186:187], v[102:103] op_sel_hi:[1,0,1]
	v_pk_fma_f32 v[100:101], v[136:137], v[186:187], v[100:101] op_sel_hi:[1,0,1] neg_lo:[1,0,0] neg_hi:[1,0,0]
	v_pk_fma_f32 v[98:99], v[186:187], v[98:99], v[134:135] op_sel:[1,0,0]
	v_pk_fma_f32 v[96:97], v[186:187], v[96:97], v[132:133] op_sel:[1,0,0]
	v_mul_f32_e32 v107, v107, v107
	v_lshl_add_u64 v[108:109], v[108:109], 0, v[176:177]
	v_pk_fma_f32 v[102:103], v[186:187], v[102:103], v[142:143] op_sel:[1,0,0]
	v_pk_fma_f32 v[100:101], v[186:187], v[100:101], v[140:141] op_sel:[1,0,0]
	v_max_f32_e32 v96, 0, v96
	v_max_f32_e32 v97, 0, v97
	v_max_f32_e32 v98, 0, v98
	v_cvt_pk_bf16_f32 v107, v110, v107
	global_store_dwordx4 v[108:109], v[104:107], off nt
	v_max_f32_e32 v100, 0, v100
	v_max_f32_e32 v99, 0, v99
	v_mul_f32_e32 v104, v96, v96
	v_max_f32_e32 v96, 0, v101
	v_mul_f32_e32 v101, v97, v97
	v_max_f32_e32 v97, 0, v102
	v_mul_f32_e32 v102, v98, v98
	v_max_f32_e32 v98, 0, v103
	v_mul_f32_e32 v100, v100, v100
	v_mul_f32_e32 v96, v96, v96
	v_mul_f32_e32 v97, v97, v97
	v_mul_f32_e32 v98, v98, v98
	v_mul_f32_e32 v99, v99, v99
	v_cvt_pk_bf16_f32 v96, v100, v96
	v_cvt_pk_bf16_f32 v97, v97, v98
	v_cvt_pk_bf16_f32 v98, v104, v101
	v_cvt_pk_bf16_f32 v99, v102, v99
	ds_read2_b64 v[100:103], v175 offset0:32 offset1:48
	global_store_dwordx4 v[108:109], v[96:99], off offset:256 nt
	v_max_f32_e32 v138, 0, v138
	v_max_f32_e32 v139, 0, v139
	v_add_u32_e32 v96, 32, v174
	s_waitcnt lgkmcnt(0)
	v_pk_fma_f32 v[90:91], v[124:125], v[100:101], v[90:91] op_sel_hi:[1,0,1]
	v_pk_fma_f32 v[88:89], v[144:145], v[100:101], v[88:89] op_sel_hi:[1,0,1] neg_lo:[1,0,0] neg_hi:[1,0,0]
	v_pk_fma_f32 v[94:95], v[150:151], v[100:101], v[94:95] op_sel_hi:[1,0,1]
	v_pk_fma_f32 v[92:93], v[148:149], v[100:101], v[92:93] op_sel_hi:[1,0,1] neg_lo:[1,0,0] neg_hi:[1,0,0]
	v_pk_fma_f32 v[90:91], v[100:101], v[90:91], v[154:155] op_sel:[1,0,0]
	v_pk_fma_f32 v[88:89], v[100:101], v[88:89], v[152:153] op_sel:[1,0,0]
	v_pk_fma_f32 v[94:95], v[100:101], v[94:95], v[158:159] op_sel:[1,0,0]
	v_pk_fma_f32 v[92:93], v[100:101], v[92:93], v[156:157] op_sel:[1,0,0]
	v_max_f32_e32 v88, 0, v88
	v_max_f32_e32 v89, 0, v89
	v_max_f32_e32 v90, 0, v90
	v_ashrrev_i32_e32 v97, 31, v96
	v_max_f32_e32 v92, 0, v92
	v_mul_f32_e32 v98, v88, v88
	v_max_f32_e32 v88, 0, v93
	v_mul_f32_e32 v93, v89, v89
	v_max_f32_e32 v89, 0, v94
	v_mul_f32_e32 v94, v90, v90
	v_max_f32_e32 v90, 0, v95
	v_lshl_add_u64 v[96:97], v[96:97], 0, s[20:21]
	v_mul_f32_e32 v92, v92, v92
	v_mul_f32_e32 v88, v88, v88
	v_mul_f32_e32 v89, v89, v89
	v_mul_f32_e32 v90, v90, v90
	v_cvt_pk_bf16_f32 v88, v92, v88
	v_cvt_pk_bf16_f32 v89, v89, v90
	v_cvt_pk_bf16_f32 v90, v98, v93
	v_lshlrev_b64 v[92:93], 13, v[96:97]
	v_pk_fma_f32 v[80:81], v[128:129], v[100:101], v[80:81] op_sel_hi:[1,0,1] neg_lo:[1,0,0] neg_hi:[1,0,0]
	v_max_f32_e32 v91, 0, v91
	v_lshl_add_u64 v[92:93], s[44:45], 0, v[92:93]
	v_pk_fma_f32 v[84:85], v[136:137], v[100:101], v[84:85] op_sel_hi:[1,0,1] neg_lo:[1,0,0] neg_hi:[1,0,0]
	v_pk_fma_f32 v[82:83], v[116:117], v[100:101], v[82:83] op_sel_hi:[1,0,1]
	v_pk_fma_f32 v[80:81], v[100:101], v[80:81], v[132:133] op_sel:[1,0,0]
	v_mul_f32_e32 v91, v91, v91
	v_lshl_add_u64 v[92:93], v[92:93], 0, v[176:177]
	v_pk_fma_f32 v[86:87], v[120:121], v[100:101], v[86:87] op_sel_hi:[1,0,1]
	v_pk_fma_f32 v[84:85], v[100:101], v[84:85], v[140:141] op_sel:[1,0,0]
	v_pk_fma_f32 v[82:83], v[100:101], v[82:83], v[134:135] op_sel:[1,0,0]
	v_max_f32_e32 v80, 0, v80
	v_cvt_pk_bf16_f32 v91, v94, v91
	global_store_dwordx4 v[92:93], v[88:91], off nt
	v_pk_fma_f32 v[86:87], v[100:101], v[86:87], v[142:143] op_sel:[1,0,0]
	v_max_f32_e32 v81, 0, v81
	v_mul_f32_e32 v88, v80, v80
	v_max_f32_e32 v80, 0, v85
	v_max_f32_e32 v82, 0, v82
	v_max_f32_e32 v84, 0, v84
	v_mul_f32_e32 v80, v80, v80
	v_mul_f32_e32 v85, v81, v81
	v_max_f32_e32 v81, 0, v86
	v_mul_f32_e32 v86, v82, v82
	v_max_f32_e32 v82, 0, v87
	v_max_f32_e32 v83, 0, v83
	v_pk_fma_f32 v[74:75], v[124:125], v[102:103], v[74:75] op_sel_hi:[1,0,1]
	v_pk_fma_f32 v[72:73], v[144:145], v[102:103], v[72:73] op_sel_hi:[1,0,1] neg_lo:[1,0,0] neg_hi:[1,0,0]
	v_mul_f32_e32 v84, v84, v84
	v_mul_f32_e32 v81, v81, v81
	v_mul_f32_e32 v82, v82, v82
	v_mul_f32_e32 v83, v83, v83
	v_cvt_pk_bf16_f32 v80, v84, v80
	v_pk_fma_f32 v[78:79], v[150:151], v[102:103], v[78:79] op_sel_hi:[1,0,1]
	v_pk_fma_f32 v[76:77], v[148:149], v[102:103], v[76:77] op_sel_hi:[1,0,1] neg_lo:[1,0,0] neg_hi:[1,0,0]
	v_pk_fma_f32 v[74:75], v[102:103], v[74:75], v[154:155] op_sel:[1,0,0]
	v_pk_fma_f32 v[72:73], v[102:103], v[72:73], v[152:153] op_sel:[1,0,0]
	v_cvt_pk_bf16_f32 v81, v81, v82
	v_cvt_pk_bf16_f32 v82, v88, v85
	v_cvt_pk_bf16_f32 v83, v86, v83
	global_store_dwordx4 v[92:93], v[80:83], off offset:256 nt
	v_pk_fma_f32 v[78:79], v[102:103], v[78:79], v[158:159] op_sel:[1,0,0]
	v_pk_fma_f32 v[76:77], v[102:103], v[76:77], v[156:157] op_sel:[1,0,0]
	v_add_u32_e32 v80, 48, v174
	v_max_f32_e32 v72, 0, v72
	v_max_f32_e32 v73, 0, v73
	v_max_f32_e32 v74, 0, v74
	v_ashrrev_i32_e32 v81, 31, v80
	v_max_f32_e32 v76, 0, v76
	v_mul_f32_e32 v82, v72, v72
	v_max_f32_e32 v72, 0, v77
	v_mul_f32_e32 v77, v73, v73
	v_max_f32_e32 v73, 0, v78
	v_mul_f32_e32 v78, v74, v74
	v_max_f32_e32 v74, 0, v79
	v_lshl_add_u64 v[80:81], v[80:81], 0, s[20:21]
	v_mul_f32_e32 v76, v76, v76
	v_mul_f32_e32 v72, v72, v72
	v_mul_f32_e32 v73, v73, v73
	v_mul_f32_e32 v74, v74, v74
	v_cvt_pk_bf16_f32 v72, v76, v72
	v_cvt_pk_bf16_f32 v73, v73, v74
	v_cvt_pk_bf16_f32 v74, v82, v77
	v_lshlrev_b64 v[76:77], 13, v[80:81]
	v_pk_fma_f32 v[66:67], v[116:117], v[102:103], v[66:67] op_sel_hi:[1,0,1]
; #define EPI_FOR_ROWS for (int ai = 0; ai < 2; ++ai) _Pragma("unroll") for (int m = 0; m < 4; ++m)
; __device__ __forceinline__ u32x4 pack8(const f32x4 a, const f32x4 b) { u32x4 w; w.x = cvt_pk_bf16(a[0], a[1]); w.y = cvt_pk_bf16(a[2], a[3]); w.z = cvt_pk_bf16(b[0], b[1]); w.w = cvt_pk_bf16(b[2], b[3]); return w; }
;     __device__ __forceinline__ void piece(size_t row, int col, f32x4 v0, f32x4 v1, const f32x4 a0, const f32x4 a1, const f32x4 b0, const f32x4 b1, const f32x4 c0, const f32x4 c1,
;                                           float mean, float rstd, float& s, float& ss) const {
;     ...
;         if constexpr (MODE == 4) { v0 = (v0 - a0 * mean) * rstd + b0; v1 = (v1 - a1 * mean) * rstd + b1;
; #pragma unroll
;             for (int e = 0; e < 4; ++e) { const float x = fmaxf(v0[e], 0.f), y = fmaxf(v1[e], 0.f); v0[e] = x * x; v1[e] = y * y; } }
;         if constexpr (PROD) {
; #pragma unroll
;             for (int e = 0; e < 4; ++e) { s += v0[e] + v1[e]; ss += v0[e] * v0[e] + v1[e] * v1[e]; } }
;         if constexpr (MODE == 5) { float* o = (float*)O + row * ldo + col; *(f32x4*)o = v0; *(f32x4*)(o + 4) = v1; }
;         else *(u32x4*)((bf16_t*)O + row * ldo + col) = pack8(v0, v1);
;     __device__ __forceinline__ void operator()(const f32x4 (&acc)[2][2][4][2], const Unit& u, int wr, int wc, int fr_, int fq_, LAS unsigned char* ldsx) const {
;     ...
;         EPI_FOR_ROWS {
;             const int rl = ai * HALF + wr * 64 + m * 16 + fr; const size_t row = (size_t)u.row0 + rl;
;             float mean = 0.f, rstd = 0.f; if constexpr (CONS) { const f32x2 st = X[rl]; mean = st.x; rstd = st.y; }
;             float s = 0.f, ss = 0.f;
; #pragma unroll
;             for (int bj = 0; bj < 2; ++bj) piece(row, colb + bj * HALF, acc[ai][bj][m][0], acc[ai][bj][m][1], av[bj][0], av[bj][1], bv[bj][0], bv[bj][1], cv[bj][0], cv[bj][1], mean, rstd, s, ss);
;             if constexpr (PROD) { s += __shfl_xor(s, 16); ss += __shfl_xor(ss, 16); s += __shfl_xor(s, 32); ss += __shfl_xor(ss, 32);
;                 if (fq == 0) st_out[row * 16 + (u.col0 >> 8) * 4 + wc] = (f32x2){s, ss}; }
	v_pk_fma_f32 v[64:65], v[128:129], v[102:103], v[64:65] op_sel_hi:[1,0,1] neg_lo:[1,0,0] neg_hi:[1,0,0]
	v_max_f32_e32 v75, 0, v75
	v_lshl_add_u64 v[76:77], s[44:45], 0, v[76:77]
	v_pk_fma_f32 v[70:71], v[120:121], v[102:103], v[70:71] op_sel_hi:[1,0,1]
	v_pk_fma_f32 v[68:69], v[136:137], v[102:103], v[68:69] op_sel_hi:[1,0,1] neg_lo:[1,0,0] neg_hi:[1,0,0]
	v_pk_fma_f32 v[66:67], v[102:103], v[66:67], v[134:135] op_sel:[1,0,0]
	v_pk_fma_f32 v[64:65], v[102:103], v[64:65], v[132:133] op_sel:[1,0,0]
	v_mul_f32_e32 v75, v75, v75
	v_lshl_add_u64 v[76:77], v[76:77], 0, v[176:177]
	v_pk_fma_f32 v[70:71], v[102:103], v[70:71], v[142:143] op_sel:[1,0,0]
	v_pk_fma_f32 v[68:69], v[102:103], v[68:69], v[140:141] op_sel:[1,0,0]
	v_max_f32_e32 v64, 0, v64
	v_max_f32_e32 v65, 0, v65
	v_max_f32_e32 v66, 0, v66
	v_cvt_pk_bf16_f32 v75, v78, v75
	global_store_dwordx4 v[76:77], v[72:75], off nt
	v_max_f32_e32 v68, 0, v68
	v_max_f32_e32 v67, 0, v67
	v_mul_f32_e32 v72, v64, v64
	v_max_f32_e32 v64, 0, v69
	v_mul_f32_e32 v69, v65, v65
	v_max_f32_e32 v65, 0, v70
	v_mul_f32_e32 v70, v66, v66
	v_max_f32_e32 v66, 0, v71
	v_mul_f32_e32 v68, v68, v68
	v_mul_f32_e32 v64, v64, v64
	v_mul_f32_e32 v65, v65, v65
	v_mul_f32_e32 v66, v66, v66
	v_mul_f32_e32 v67, v67, v67
	v_cvt_pk_bf16_f32 v64, v68, v64
	v_cvt_pk_bf16_f32 v65, v65, v66
	v_cvt_pk_bf16_f32 v66, v72, v69
	v_cvt_pk_bf16_f32 v67, v70, v67
	ds_read2_b64 v[68:71], v175 offset0:128 offset1:144
	global_store_dwordx4 v[76:77], v[64:67], off offset:256 nt
	v_max_f32_e32 v119, 0, v119
	v_mul_f32_e32 v138, v138, v138
	v_add_u32_e32 v64, 0x80, v174
	s_waitcnt lgkmcnt(0)
	v_pk_fma_f32 v[58:59], v[124:125], v[68:69], v[58:59] op_sel_hi:[1,0,1]
	v_pk_fma_f32 v[56:57], v[144:145], v[68:69], v[56:57] op_sel_hi:[1,0,1] neg_lo:[1,0,0] neg_hi:[1,0,0]
	v_pk_fma_f32 v[62:63], v[150:151], v[68:69], v[62:63] op_sel_hi:[1,0,1]
	v_pk_fma_f32 v[60:61], v[148:149], v[68:69], v[60:61] op_sel_hi:[1,0,1] neg_lo:[1,0,0] neg_hi:[1,0,0]
	v_pk_fma_f32 v[58:59], v[68:69], v[58:59], v[154:155] op_sel:[1,0,0]
	v_pk_fma_f32 v[56:57], v[68:69], v[56:57], v[152:153] op_sel:[1,0,0]
	v_pk_fma_f32 v[62:63], v[68:69], v[62:63], v[158:159] op_sel:[1,0,0]
	v_pk_fma_f32 v[60:61], v[68:69], v[60:61], v[156:157] op_sel:[1,0,0]
	v_max_f32_e32 v56, 0, v56
	v_max_f32_e32 v57, 0, v57
	v_max_f32_e32 v58, 0, v58
	v_ashrrev_i32_e32 v65, 31, v64
	v_max_f32_e32 v60, 0, v60
	v_mul_f32_e32 v66, v56, v56
	v_max_f32_e32 v56, 0, v61
	v_mul_f32_e32 v61, v57, v57
	v_max_f32_e32 v57, 0, v62
	v_mul_f32_e32 v62, v58, v58
	v_max_f32_e32 v58, 0, v63
	v_lshl_add_u64 v[64:65], v[64:65], 0, s[20:21]
	v_mul_f32_e32 v60, v60, v60
	v_mul_f32_e32 v56, v56, v56
	v_mul_f32_e32 v57, v57, v57
	v_mul_f32_e32 v58, v58, v58
	v_cvt_pk_bf16_f32 v56, v60, v56
	v_cvt_pk_bf16_f32 v57, v57, v58
	v_cvt_pk_bf16_f32 v58, v66, v61
	v_lshlrev_b64 v[60:61], 13, v[64:65]
	v_pk_fma_f32 v[48:49], v[128:129], v[68:69], v[48:49] op_sel_hi:[1,0,1] neg_lo:[1,0,0] neg_hi:[1,0,0]
	v_max_f32_e32 v59, 0, v59
	v_lshl_add_u64 v[60:61], s[44:45], 0, v[60:61]
	v_pk_fma_f32 v[52:53], v[136:137], v[68:69], v[52:53] op_sel_hi:[1,0,1] neg_lo:[1,0,0] neg_hi:[1,0,0]
	v_pk_fma_f32 v[50:51], v[116:117], v[68:69], v[50:51] op_sel_hi:[1,0,1]
	v_pk_fma_f32 v[48:49], v[68:69], v[48:49], v[132:133] op_sel:[1,0,0]
	v_mul_f32_e32 v59, v59, v59
	v_lshl_add_u64 v[60:61], v[60:61], 0, v[176:177]
	v_pk_fma_f32 v[54:55], v[120:121], v[68:69], v[54:55] op_sel_hi:[1,0,1]
	v_pk_fma_f32 v[52:53], v[68:69], v[52:53], v[140:141] op_sel:[1,0,0]
	v_pk_fma_f32 v[50:51], v[68:69], v[50:51], v[134:135] op_sel:[1,0,0]
	v_max_f32_e32 v48, 0, v48
	v_cvt_pk_bf16_f32 v59, v62, v59
	global_store_dwordx4 v[60:61], v[56:59], off nt
	v_pk_fma_f32 v[54:55], v[68:69], v[54:55], v[142:143] op_sel:[1,0,0]
	v_max_f32_e32 v49, 0, v49
	v_mul_f32_e32 v56, v48, v48
	v_max_f32_e32 v48, 0, v53
	v_max_f32_e32 v50, 0, v50
	v_max_f32_e32 v52, 0, v52
	v_mul_f32_e32 v48, v48, v48
	v_mul_f32_e32 v53, v49, v49
	v_max_f32_e32 v49, 0, v54
	v_mul_f32_e32 v54, v50, v50
	v_max_f32_e32 v50, 0, v55
	v_max_f32_e32 v51, 0, v51
	v_pk_fma_f32 v[42:43], v[124:125], v[70:71], v[42:43] op_sel_hi:[1,0,1]
	v_pk_fma_f32 v[40:41], v[144:145], v[70:71], v[40:41] op_sel_hi:[1,0,1] neg_lo:[1,0,0] neg_hi:[1,0,0]
	v_mul_f32_e32 v52, v52, v52
	v_mul_f32_e32 v49, v49, v49
	v_mul_f32_e32 v50, v50, v50
	v_mul_f32_e32 v51, v51, v51
	v_cvt_pk_bf16_f32 v48, v52, v48
	v_pk_fma_f32 v[46:47], v[150:151], v[70:71], v[46:47] op_sel_hi:[1,0,1]
	v_pk_fma_f32 v[44:45], v[148:149], v[70:71], v[44:45] op_sel_hi:[1,0,1] neg_lo:[1,0,0] neg_hi:[1,0,0]
	v_pk_fma_f32 v[42:43], v[70:71], v[42:43], v[154:155] op_sel:[1,0,0]
	v_pk_fma_f32 v[40:41], v[70:71], v[40:41], v[152:153] op_sel:[1,0,0]
	v_cvt_pk_bf16_f32 v49, v49, v50
	v_cvt_pk_bf16_f32 v50, v56, v53
	v_cvt_pk_bf16_f32 v51, v54, v51
	global_store_dwordx4 v[60:61], v[48:51], off offset:256 nt
	v_pk_fma_f32 v[46:47], v[70:71], v[46:47], v[158:159] op_sel:[1,0,0]
	v_pk_fma_f32 v[44:45], v[70:71], v[44:45], v[156:157] op_sel:[1,0,0]
	v_add_u32_e32 v48, 0x90, v174
	v_max_f32_e32 v40, 0, v40
	v_max_f32_e32 v41, 0, v41
	v_max_f32_e32 v42, 0, v42
	v_ashrrev_i32_e32 v49, 31, v48
	v_max_f32_e32 v44, 0, v44
	v_mul_f32_e32 v50, v40, v40
	v_max_f32_e32 v40, 0, v45
	v_mul_f32_e32 v45, v41, v41
	v_max_f32_e32 v41, 0, v46
	v_mul_f32_e32 v46, v42, v42
	v_max_f32_e32 v42, 0, v47
	v_lshl_add_u64 v[48:49], v[48:49], 0, s[20:21]
	v_mul_f32_e32 v44, v44, v44
	v_mul_f32_e32 v40, v40, v40
	v_mul_f32_e32 v41, v41, v41
	v_mul_f32_e32 v42, v42, v42
	v_cvt_pk_bf16_f32 v40, v44, v40
	v_cvt_pk_bf16_f32 v41, v41, v42
	v_cvt_pk_bf16_f32 v42, v50, v45
	v_lshlrev_b64 v[44:45], 13, v[48:49]
; __device__ __forceinline__ u32x4 pack8(const f32x4 a, const f32x4 b) { u32x4 w; w.x = cvt_pk_bf16(a[0], a[1]); w.y = cvt_pk_bf16(a[2], a[3]); w.z = cvt_pk_bf16(b[0], b[1]); w.w = cvt_pk_bf16(b[2], b[3]); return w; }
;     __device__ __forceinline__ void piece(size_t row, int col, f32x4 v0, f32x4 v1, const f32x4 a0, const f32x4 a1, const f32x4 b0, const f32x4 b1, const f32x4 c0, const f32x4 c1,
;                                           float mean, float rstd, float& s, float& ss) const {
;     ...
;         if constexpr (MODE == 4) { v0 = (v0 - a0 * mean) * rstd + b0; v1 = (v1 - a1 * mean) * rstd + b1;
; #pragma unroll
;             for (int e = 0; e < 4; ++e) { const float x = fmaxf(v0[e], 0.f), y = fmaxf(v1[e], 0.f); v0[e] = x * x; v1[e] = y * y; } }
;         if constexpr (PROD) {
; #pragma unroll
;             for (int e = 0; e < 4; ++e) { s += v0[e] + v1[e]; ss += v0[e] * v0[e] + v1[e] * v1[e]; } }
;         if constexpr (MODE == 5) { float* o = (float*)O + row * ldo + col; *(f32x4*)o = v0; *(f32x4*)(o + 4) = v1; }
;         else *(u32x4*)((bf16_t*)O + row * ldo + col) = pack8(v0, v1);
	v_pk_fma_f32 v[34:35], v[116:117], v[70:71], v[34:35] op_sel_hi:[1,0,1]
	v_pk_fma_f32 v[32:33], v[128:129], v[70:71], v[32:33] op_sel_hi:[1,0,1] neg_lo:[1,0,0] neg_hi:[1,0,0]
	v_max_f32_e32 v43, 0, v43
	v_lshl_add_u64 v[44:45], s[44:45], 0, v[44:45]
	v_pk_fma_f32 v[38:39], v[120:121], v[70:71], v[38:39] op_sel_hi:[1,0,1]
	v_pk_fma_f32 v[36:37], v[136:137], v[70:71], v[36:37] op_sel_hi:[1,0,1] neg_lo:[1,0,0] neg_hi:[1,0,0]
	v_pk_fma_f32 v[34:35], v[70:71], v[34:35], v[134:135] op_sel:[1,0,0]
	v_pk_fma_f32 v[32:33], v[70:71], v[32:33], v[132:133] op_sel:[1,0,0]
	v_mul_f32_e32 v43, v43, v43
	v_lshl_add_u64 v[44:45], v[44:45], 0, v[176:177]
	v_pk_fma_f32 v[38:39], v[70:71], v[38:39], v[142:143] op_sel:[1,0,0]
	v_pk_fma_f32 v[36:37], v[70:71], v[36:37], v[140:141] op_sel:[1,0,0]
	v_max_f32_e32 v32, 0, v32
	v_max_f32_e32 v33, 0, v33
	v_max_f32_e32 v34, 0, v34
	v_cvt_pk_bf16_f32 v43, v46, v43
	global_store_dwordx4 v[44:45], v[40:43], off nt
	v_max_f32_e32 v36, 0, v36
	v_max_f32_e32 v35, 0, v35
	v_mul_f32_e32 v40, v32, v32
	v_max_f32_e32 v32, 0, v37
	v_mul_f32_e32 v37, v33, v33
	v_max_f32_e32 v33, 0, v38
	v_mul_f32_e32 v38, v34, v34
	v_max_f32_e32 v34, 0, v39
	v_mul_f32_e32 v36, v36, v36
	v_mul_f32_e32 v32, v32, v32
	v_mul_f32_e32 v33, v33, v33
	v_mul_f32_e32 v34, v34, v34
	v_mul_f32_e32 v35, v35, v35
	v_cvt_pk_bf16_f32 v32, v36, v32
	v_cvt_pk_bf16_f32 v33, v33, v34
	v_cvt_pk_bf16_f32 v34, v40, v37
	v_cvt_pk_bf16_f32 v35, v38, v35
	ds_read2_b64 v[36:39], v175 offset0:160 offset1:176
	global_store_dwordx4 v[44:45], v[32:35], off offset:256 nt
	v_mul_f32_e32 v139, v139, v139
	v_mul_f32_e32 v118, v118, v118
	v_add_u32_e32 v32, 0xa0, v174
	s_waitcnt lgkmcnt(0)
; #define EPI_FOR_ROWS for (int ai = 0; ai < 2; ++ai) _Pragma("unroll") for (int m = 0; m < 4; ++m)
; __device__ __forceinline__ u32x4 pack8(const f32x4 a, const f32x4 b) { u32x4 w; w.x = cvt_pk_bf16(a[0], a[1]); w.y = cvt_pk_bf16(a[2], a[3]); w.z = cvt_pk_bf16(b[0], b[1]); w.w = cvt_pk_bf16(b[2], b[3]); return w; }
;     __device__ __forceinline__ void piece(size_t row, int col, f32x4 v0, f32x4 v1, const f32x4 a0, const f32x4 a1, const f32x4 b0, const f32x4 b1, const f32x4 c0, const f32x4 c1,
;                                           float mean, float rstd, float& s, float& ss) const {
;     ...
;         if constexpr (MODE == 4) { v0 = (v0 - a0 * mean) * rstd + b0; v1 = (v1 - a1 * mean) * rstd + b1;
; #pragma unroll
;             for (int e = 0; e < 4; ++e) { const float x = fmaxf(v0[e], 0.f), y = fmaxf(v1[e], 0.f); v0[e] = x * x; v1[e] = y * y; } }
;         if constexpr (PROD) {
; #pragma unroll
;             for (int e = 0; e < 4; ++e) { s += v0[e] + v1[e]; ss += v0[e] * v0[e] + v1[e] * v1[e]; } }
;         if constexpr (MODE == 5) { float* o = (float*)O + row * ldo + col; *(f32x4*)o = v0; *(f32x4*)(o + 4) = v1; }
;         else *(u32x4*)((bf16_t*)O + row * ldo + col) = pack8(v0, v1);
;     __device__ __forceinline__ void operator()(const f32x4 (&acc)[2][2][4][2], const Unit& u, int wr, int wc, int fr_, int fq_, LAS unsigned char* ldsx) const {
;     ...
;         EPI_FOR_ROWS {
;             const int rl = ai * HALF + wr * 64 + m * 16 + fr; const size_t row = (size_t)u.row0 + rl;
;             float mean = 0.f, rstd = 0.f; if constexpr (CONS) { const f32x2 st = X[rl]; mean = st.x; rstd = st.y; }
;             float s = 0.f, ss = 0.f;
; #pragma unroll
;             for (int bj = 0; bj < 2; ++bj) piece(row, colb + bj * HALF, acc[ai][bj][m][0], acc[ai][bj][m][1], av[bj][0], av[bj][1], bv[bj][0], bv[bj][1], cv[bj][0], cv[bj][1], mean, rstd, s, ss);
;             if constexpr (PROD) { s += __shfl_xor(s, 16); ss += __shfl_xor(ss, 16); s += __shfl_xor(s, 32); ss += __shfl_xor(ss, 32);
;                 if (fq == 0) st_out[row * 16 + (u.col0 >> 8) * 4 + wc] = (f32x2){s, ss}; }
	v_pk_fma_f32 v[26:27], v[124:125], v[36:37], v[26:27] op_sel_hi:[1,0,1]
	v_pk_fma_f32 v[24:25], v[144:145], v[36:37], v[24:25] op_sel_hi:[1,0,1] neg_lo:[1,0,0] neg_hi:[1,0,0]
	v_pk_fma_f32 v[30:31], v[150:151], v[36:37], v[30:31] op_sel_hi:[1,0,1]
	v_pk_fma_f32 v[28:29], v[148:149], v[36:37], v[28:29] op_sel_hi:[1,0,1] neg_lo:[1,0,0] neg_hi:[1,0,0]
	v_pk_fma_f32 v[26:27], v[36:37], v[26:27], v[154:155] op_sel:[1,0,0]
	v_pk_fma_f32 v[24:25], v[36:37], v[24:25], v[152:153] op_sel:[1,0,0]
	v_pk_fma_f32 v[30:31], v[36:37], v[30:31], v[158:159] op_sel:[1,0,0]
	v_pk_fma_f32 v[28:29], v[36:37], v[28:29], v[156:157] op_sel:[1,0,0]
	v_max_f32_e32 v24, 0, v24
	v_max_f32_e32 v25, 0, v25
	v_max_f32_e32 v26, 0, v26
	v_ashrrev_i32_e32 v33, 31, v32
	v_max_f32_e32 v28, 0, v28
	v_mul_f32_e32 v34, v24, v24
	v_max_f32_e32 v24, 0, v29
	v_mul_f32_e32 v29, v25, v25
	v_max_f32_e32 v25, 0, v30
	v_mul_f32_e32 v30, v26, v26
	v_max_f32_e32 v26, 0, v31
	v_lshl_add_u64 v[32:33], v[32:33], 0, s[20:21]
	v_mul_f32_e32 v28, v28, v28
	v_mul_f32_e32 v24, v24, v24
	v_mul_f32_e32 v25, v25, v25
	v_mul_f32_e32 v26, v26, v26
	v_cvt_pk_bf16_f32 v24, v28, v24
	v_cvt_pk_bf16_f32 v25, v25, v26
	v_cvt_pk_bf16_f32 v26, v34, v29
	v_lshlrev_b64 v[28:29], 13, v[32:33]
	v_pk_fma_f32 v[16:17], v[128:129], v[36:37], v[16:17] op_sel_hi:[1,0,1] neg_lo:[1,0,0] neg_hi:[1,0,0]
	v_max_f32_e32 v27, 0, v27
	v_lshl_add_u64 v[28:29], s[44:45], 0, v[28:29]
	v_pk_fma_f32 v[20:21], v[136:137], v[36:37], v[20:21] op_sel_hi:[1,0,1] neg_lo:[1,0,0] neg_hi:[1,0,0]
	v_pk_fma_f32 v[18:19], v[116:117], v[36:37], v[18:19] op_sel_hi:[1,0,1]
	v_pk_fma_f32 v[16:17], v[36:37], v[16:17], v[132:133] op_sel:[1,0,0]
	v_mul_f32_e32 v27, v27, v27
	v_lshl_add_u64 v[28:29], v[28:29], 0, v[176:177]
	v_pk_fma_f32 v[22:23], v[120:121], v[36:37], v[22:23] op_sel_hi:[1,0,1]
	v_pk_fma_f32 v[20:21], v[36:37], v[20:21], v[140:141] op_sel:[1,0,0]
	v_pk_fma_f32 v[18:19], v[36:37], v[18:19], v[134:135] op_sel:[1,0,0]
	v_max_f32_e32 v16, 0, v16
	v_cvt_pk_bf16_f32 v27, v30, v27
	global_store_dwordx4 v[28:29], v[24:27], off nt
	v_pk_fma_f32 v[22:23], v[36:37], v[22:23], v[142:143] op_sel:[1,0,0]
	v_max_f32_e32 v17, 0, v17
	v_mul_f32_e32 v24, v16, v16
	v_max_f32_e32 v16, 0, v21
	v_max_f32_e32 v18, 0, v18
	v_max_f32_e32 v20, 0, v20
	v_mul_f32_e32 v16, v16, v16
	v_mul_f32_e32 v21, v17, v17
	v_max_f32_e32 v17, 0, v22
	v_mul_f32_e32 v22, v18, v18
	v_max_f32_e32 v18, 0, v23
	v_max_f32_e32 v19, 0, v19
	v_pk_fma_f32 v[10:11], v[124:125], v[38:39], v[10:11] op_sel_hi:[1,0,1]
	v_pk_fma_f32 v[8:9], v[144:145], v[38:39], v[8:9] op_sel_hi:[1,0,1] neg_lo:[1,0,0] neg_hi:[1,0,0]
	v_mul_f32_e32 v20, v20, v20
	v_mul_f32_e32 v17, v17, v17
	v_mul_f32_e32 v18, v18, v18
	v_mul_f32_e32 v19, v19, v19
	v_cvt_pk_bf16_f32 v16, v20, v16
	v_pk_fma_f32 v[14:15], v[150:151], v[38:39], v[14:15] op_sel_hi:[1,0,1]
	v_pk_fma_f32 v[12:13], v[148:149], v[38:39], v[12:13] op_sel_hi:[1,0,1] neg_lo:[1,0,0] neg_hi:[1,0,0]
	v_pk_fma_f32 v[10:11], v[38:39], v[10:11], v[154:155] op_sel:[1,0,0]
	v_pk_fma_f32 v[8:9], v[38:39], v[8:9], v[152:153] op_sel:[1,0,0]
	v_cvt_pk_bf16_f32 v17, v17, v18
	v_cvt_pk_bf16_f32 v18, v24, v21
	v_cvt_pk_bf16_f32 v19, v22, v19
	global_store_dwordx4 v[28:29], v[16:19], off offset:256 nt
	v_pk_fma_f32 v[14:15], v[38:39], v[14:15], v[158:159] op_sel:[1,0,0]
	v_pk_fma_f32 v[12:13], v[38:39], v[12:13], v[156:157] op_sel:[1,0,0]
	v_add_u32_e32 v16, 0xb0, v174
	v_max_f32_e32 v8, 0, v8
	v_max_f32_e32 v9, 0, v9
	v_max_f32_e32 v10, 0, v10
	v_ashrrev_i32_e32 v17, 31, v16
	v_max_f32_e32 v12, 0, v12
	v_mul_f32_e32 v18, v8, v8
	v_max_f32_e32 v8, 0, v13
	v_mul_f32_e32 v13, v9, v9
	v_max_f32_e32 v9, 0, v14
	v_mul_f32_e32 v14, v10, v10
	v_max_f32_e32 v10, 0, v15
	v_lshl_add_u64 v[16:17], v[16:17], 0, s[20:21]
	v_mul_f32_e32 v12, v12, v12
	v_mul_f32_e32 v8, v8, v8
	v_mul_f32_e32 v9, v9, v9
	v_mul_f32_e32 v10, v10, v10
	v_cvt_pk_bf16_f32 v8, v12, v8
	v_cvt_pk_bf16_f32 v9, v9, v10
	v_cvt_pk_bf16_f32 v10, v18, v13
	v_lshlrev_b64 v[12:13], 13, v[16:17]
	v_pk_fma_f32 v[2:3], v[116:117], v[38:39], v[2:3] op_sel_hi:[1,0,1]
	v_pk_fma_f32 v[0:1], v[128:129], v[38:39], v[0:1] op_sel_hi:[1,0,1] neg_lo:[1,0,0] neg_hi:[1,0,0]
	v_max_f32_e32 v11, 0, v11
	v_lshl_add_u64 v[12:13], s[44:45], 0, v[12:13]
	v_pk_fma_f32 v[6:7], v[120:121], v[38:39], v[6:7] op_sel_hi:[1,0,1]
	v_pk_fma_f32 v[4:5], v[136:137], v[38:39], v[4:5] op_sel_hi:[1,0,1] neg_lo:[1,0,0] neg_hi:[1,0,0]
	v_pk_fma_f32 v[2:3], v[38:39], v[2:3], v[134:135] op_sel:[1,0,0]
	v_pk_fma_f32 v[0:1], v[38:39], v[0:1], v[132:133] op_sel:[1,0,0]
	v_mul_f32_e32 v11, v11, v11
	v_lshl_add_u64 v[12:13], v[12:13], 0, v[176:177]
	v_pk_fma_f32 v[6:7], v[38:39], v[6:7], v[142:143] op_sel:[1,0,0]
	v_pk_fma_f32 v[4:5], v[38:39], v[4:5], v[140:141] op_sel:[1,0,0]
	v_max_f32_e32 v0, 0, v0
	v_max_f32_e32 v1, 0, v1
	v_max_f32_e32 v2, 0, v2
	v_cvt_pk_bf16_f32 v11, v14, v11
	global_store_dwordx4 v[12:13], v[8:11], off nt
	v_max_f32_e32 v3, 0, v3
	v_max_f32_e32 v4, 0, v4
	v_mul_f32_e32 v8, v0, v0
	v_max_f32_e32 v0, 0, v5
	v_mul_f32_e32 v5, v1, v1
	v_max_f32_e32 v1, 0, v6
	v_mul_f32_e32 v6, v2, v2
	v_max_f32_e32 v2, 0, v7
	v_mul_f32_e32 v0, v0, v0
	v_mul_f32_e32 v1, v1, v1
	v_mul_f32_e32 v2, v2, v2
	v_mul_f32_e32 v3, v3, v3
	s_mov_b64 s[20:21], -1
	v_mul_f32_e32 v119, v119, v119
	v_cvt_pk_bf16_f32 v188, v138, v139
	v_cvt_pk_bf16_f32 v189, v130, v119
	v_cvt_pk_bf16_f32 v190, v184, v185
	v_cvt_pk_bf16_f32 v191, v118, v131
	global_store_dwordx4 v[192:193], v[188:191], off offset:256 nt
	v_mul_f32_e32 v4, v4, v4
	v_cvt_pk_bf16_f32 v0, v4, v0
	v_cvt_pk_bf16_f32 v1, v1, v2
	v_cvt_pk_bf16_f32 v2, v8, v5
	v_cvt_pk_bf16_f32 v3, v6, v3
	global_store_dwordx4 v[12:13], v[0:3], off offset:256 nt
	s_cbranch_vccnz .LBB0_1369
	s_andn2_b64 vcc, exec, s[12:13]
	s_cbranch_vccnz .LBB0_1368
	s_barrier
	s_branch .LBB0_1368
